# HGRN pass-B recurrence loop hand-scheduled: o-chain of step t software-pipelined under the state update of step t+1, packed dot, no exec toggling for the o store
# speedup vs baseline: 1.0111x; 1.0111x over previous
.LBB0_450:
	v_mov_b32_e32 v113, v121
	v_mov_b32_e32 v114, v131
	v_mov_b32_e32 v115, v123
	v_add_u32_e32 v112, 0x10000, v131
	s_nop 0
	v_cndmask_b32_e64 v112, v112, v131, s[8:9]
	ds_read_b128 v[60:63], v113 offset:0
	ds_read_b128 v[56:59], v113 offset:16
	ds_read_b32 v88, v114 offset:0
	ds_read_b128 v[52:55], v115 offset:0
	ds_read_b128 v[48:51], v115 offset:16
	ds_read_b128 v[64:67], v113 offset:256
	ds_read_b128 v[68:71], v113 offset:272
	ds_read_b32 v90, v114 offset:256
	ds_read_b128 v[72:75], v115 offset:256
	ds_read_b128 v[76:79], v115 offset:272
	s_waitcnt lgkmcnt(5)
	v_pk_add_f32 v[92:93], v[86:87], v[88:89] op_sel_hi:[1,0] neg_lo:[0,1] neg_hi:[0,1]
	v_pk_add_f32 v[94:95], v[84:85], v[88:89] op_sel_hi:[1,0] neg_lo:[0,1] neg_hi:[0,1]
	v_pk_add_f32 v[104:105], v[82:83], v[88:89] op_sel_hi:[1,0] neg_lo:[0,1] neg_hi:[0,1]
	v_pk_add_f32 v[106:107], v[80:81], v[88:89] op_sel_hi:[1,0] neg_lo:[0,1] neg_hi:[0,1]
	v_pk_fma_f32 v[86:87], v[60:61], v[92:93], v[88:89] op_sel_hi:[1,1,0]
	v_pk_fma_f32 v[84:85], v[62:63], v[94:95], v[88:89] op_sel_hi:[1,1,0]
	v_pk_fma_f32 v[82:83], v[56:57], v[104:105], v[88:89] op_sel_hi:[1,1,0]
	v_pk_fma_f32 v[80:81], v[58:59], v[106:107], v[88:89] op_sel_hi:[1,1,0]
	s_waitcnt lgkmcnt(0)
	s_mov_b32 s1, 0
.Lhg_loop:
	s_waitcnt lgkmcnt(3)
	ds_read_b128 v[60:63], v113 offset:512
	ds_read_b128 v[56:59], v113 offset:528
	ds_read_b32 v88, v114 offset:512
	v_pk_mul_f32 v[108:109], v[52:53], v[86:87]
	v_pk_add_f32 v[92:93], v[86:87], v[90:91] op_sel_hi:[1,0] neg_lo:[0,1] neg_hi:[0,1]
	v_pk_add_f32 v[94:95], v[84:85], v[90:91] op_sel_hi:[1,0] neg_lo:[0,1] neg_hi:[0,1]
	v_pk_fma_f32 v[108:109], v[54:55], v[84:85], v[108:109]
	v_pk_add_f32 v[104:105], v[82:83], v[90:91] op_sel_hi:[1,0] neg_lo:[0,1] neg_hi:[0,1]
	v_pk_add_f32 v[106:107], v[80:81], v[90:91] op_sel_hi:[1,0] neg_lo:[0,1] neg_hi:[0,1]
	v_pk_fma_f32 v[108:109], v[48:49], v[82:83], v[108:109]
	v_pk_fma_f32 v[86:87], v[64:65], v[92:93], v[90:91] op_sel_hi:[1,1,0]
	v_pk_fma_f32 v[84:85], v[66:67], v[94:95], v[90:91] op_sel_hi:[1,1,0]
	v_pk_fma_f32 v[108:109], v[50:51], v[80:81], v[108:109]
	ds_read_b128 v[52:55], v115 offset:512
	ds_read_b128 v[48:51], v115 offset:528
	v_add_f32_e32 v110, v108, v109
	v_pk_fma_f32 v[82:83], v[68:69], v[104:105], v[90:91] op_sel_hi:[1,1,0]
	v_pk_fma_f32 v[80:81], v[70:71], v[106:107], v[90:91] op_sel_hi:[1,1,0]
	v_add_f32_dpp v110, v110, v110 quad_perm:[1,0,3,2] row_mask:0xf bank_mask:0xf bound_ctrl:1
	s_nop 1
	v_add_f32_dpp v110, v110, v110 quad_perm:[2,3,0,1] row_mask:0xf bank_mask:0xf bound_ctrl:1
	s_nop 1
	v_mov_b32_dpp v111, v110 row_half_mirror row_mask:0xf bank_mask:0xf bound_ctrl:1
	s_nop 0
	v_add_f32_e32 v110, v110, v111
	ds_write_b32 v112, v110
	s_waitcnt lgkmcnt(3)
	ds_read_b128 v[64:67], v113 offset:768
	ds_read_b128 v[68:71], v113 offset:784
	ds_read_b32 v90, v114 offset:768
	v_pk_mul_f32 v[108:109], v[72:73], v[86:87]
	v_pk_add_f32 v[92:93], v[86:87], v[88:89] op_sel_hi:[1,0] neg_lo:[0,1] neg_hi:[0,1]
	v_pk_add_f32 v[94:95], v[84:85], v[88:89] op_sel_hi:[1,0] neg_lo:[0,1] neg_hi:[0,1]
	v_pk_fma_f32 v[108:109], v[74:75], v[84:85], v[108:109]
	v_pk_add_f32 v[104:105], v[82:83], v[88:89] op_sel_hi:[1,0] neg_lo:[0,1] neg_hi:[0,1]
	v_pk_add_f32 v[106:107], v[80:81], v[88:89] op_sel_hi:[1,0] neg_lo:[0,1] neg_hi:[0,1]
	v_pk_fma_f32 v[108:109], v[76:77], v[82:83], v[108:109]
	v_pk_fma_f32 v[86:87], v[60:61], v[92:93], v[88:89] op_sel_hi:[1,1,0]
	v_pk_fma_f32 v[84:85], v[62:63], v[94:95], v[88:89] op_sel_hi:[1,1,0]
	v_pk_fma_f32 v[108:109], v[78:79], v[80:81], v[108:109]
	ds_read_b128 v[72:75], v115 offset:768
	ds_read_b128 v[76:79], v115 offset:784
	v_add_f32_e32 v110, v108, v109
	v_pk_fma_f32 v[82:83], v[56:57], v[104:105], v[88:89] op_sel_hi:[1,1,0]
	v_pk_fma_f32 v[80:81], v[58:59], v[106:107], v[88:89] op_sel_hi:[1,1,0]
	v_add_f32_dpp v110, v110, v110 quad_perm:[1,0,3,2] row_mask:0xf bank_mask:0xf bound_ctrl:1
	v_add_u32_e32 v113, 0x200, v113
	v_add_u32_e32 v114, 0x200, v114
	v_add_f32_dpp v110, v110, v110 quad_perm:[2,3,0,1] row_mask:0xf bank_mask:0xf bound_ctrl:1
	v_add_u32_e32 v115, 0x200, v115
	s_nop 0
	v_mov_b32_dpp v111, v110 row_half_mirror row_mask:0xf bank_mask:0xf bound_ctrl:1
	s_nop 0
	v_add_f32_e32 v110, v110, v111
	ds_write_b32 v112, v110 offset:256
	v_add_u32_e32 v112, 0x200, v112
	s_add_i32 s1, s1, 1
	s_cmp_lt_u32 s1, 64
	s_cbranch_scc1 .Lhg_loop
	s_waitcnt lgkmcnt(0)
	s_branch .LBB0_427
